# role B's wait for its last-slot LDS-DMAs moved from loop exit to just before its deferred barrier (epilogue starts without waiting on DMA landing)
# speedup vs baseline: 1.0037x; 1.0028x over previous
; #define PG8_BAR __builtin_amdgcn_s_barrier()
; template <class Epi, class Sched, bool ALIGN_EPI>
; __device__ __forceinline__ void gemm_phase(PG8_LAS unsigned char* lds, const Gemm g, const Sched& S, const Epi& E) {
;     ...
;                     for (int n = 0; n < 2; ++n) acc[a][b][m][n] = (f32x4){0.f, 0.f, 0.f, 0.f};
;         cur = nxt; cA = nA; cB = nB; ++ui;
;         if constexpr (ALIGN_EPI) { if (wr == 1) PG8_BAR; }
.Lp8k_B_init:
	s_setprio 1
	s_sub_u32 s28, s28, 0xa0000
	s_subb_u32 s29, s29, 0
	s_sub_u32 s50, s22, 0x20000
	s_subb_u32 s51, s23, 0
	s_cmp_eq_u32 s42, 1
	s_cbranch_scc1 .Lp8k_B_nobar
	s_waitcnt vmcnt(8)
	s_barrier

; #define PG8_STAGE(bufoff, gbase, voff) do { _Pragma("unroll") for (int _i = 0; _i < 2; ++_i) \
;         __builtin_amdgcn_global_load_lds((const unsigned*)((const char*)(gbase) + (voff)[_i]), (PG8_LAS unsigned*)(lds + (bufoff) + ldsw + _i * 8192), 16, 0, 0); } while (0)
; #define PG8_LDA(dst, b, h) do { _Pragma("unroll") for (int m = 0; m < 4; ++m) _Pragma("unroll") for (int k = 0; k < 2; ++k) dst[m][k] = *(const PG8_LAS bf16x8*)(lds + PG8_SA(b, h) + aoff + m * 2048 + k * 1024); } while (0)
; #define PG8_LDB(dst, b, h) do { _Pragma("unroll") for (int n = 0; n < 2; ++n) _Pragma("unroll") for (int k = 0; k < 2; ++k) dst[n][k] = *(const PG8_LAS bf16x8*)(lds + PG8_SB(b, h) + boff + n * 2048 + k * 1024); } while (0)
; #define PG8_MMA(ai, bj, At, Bt) do { __builtin_amdgcn_s_setprio(1); _Pragma("unroll") for (int m = 0; m < 4; ++m) _Pragma("unroll") for (int n = 0; n < 2; ++n) _Pragma("unroll") for (int k = 0; k < 2; ++k) \
;         acc[ai][bj][m][n] = __builtin_amdgcn_mfma_f32_16x16x32_bf16(Bt[n][k], At[m][k], acc[ai][bj][m][n], 0, 0, 0); __builtin_amdgcn_s_setprio(0); } while (0)
; #define PG8_WAIT_V(n) asm volatile("s_waitcnt vmcnt(" #n ")" ::: "memory")
; #define PG8_WAIT_L(n) asm volatile("s_waitcnt lgkmcnt(" #n ")" ::: "memory")
; #define PG8_BAR __builtin_amdgcn_s_barrier()
; #define PG8_SCHED __builtin_amdgcn_sched_barrier(0)
; template <class Epi, class Sched, bool ALIGN_EPI>
; __device__ __forceinline__ void gemm_phase(PG8_LAS unsigned char* lds, const Gemm g, const Sched& S, const Epi& E) {
;     ...
;             PG8_LDB(B0, 0, 0); PG8_LDB(B1, 0, 1); PG8_SCHED; PG8_LDA(At, 0, 0); PG8_STAGE(PG8_SA(1, 1), a1 + hstepA, voffA);
;             PG8_WAIT_V(8); PG8_WAIT_L(0); PG8_BAR; PG8_MMA(0, 0, At, B0); PG8_MMA(0, 1, At, B1); PG8_BAR; PG8_SCHED;
;             PG8_LDA(At, 0, 1); PG8_STAGE(PG8_SB(0, 0), b2, voffB); PG8_STAGE(PG8_SB(0, 1), b2 + hstepB, voffB); PG8_STAGE(PG8_SA(0, 0), a2, voffA);
;             PG8_WAIT_V(8); PG8_WAIT_L(0); PG8_BAR; PG8_MMA(1, 0, At, B0); PG8_MMA(1, 1, At, B1); PG8_BAR; PG8_SCHED;
;             PG8_LDB(B0, 1, 0); PG8_LDB(B1, 1, 1); PG8_SCHED; PG8_LDA(At, 1, 0); PG8_STAGE(PG8_SA(0, 1), a2 + hstepA, voffA);
;             PG8_WAIT_V(8); PG8_WAIT_L(0); PG8_BAR; PG8_MMA(0, 0, At, B0); PG8_MMA(0, 1, At, B1); PG8_BAR; PG8_SCHED;
.Lp8k_B_loop:
	ds_read_b128 v[190:193], v155 offset:0
	ds_read_b128 v[194:197], v155 offset:1024
	ds_read_b128 v[198:201], v155 offset:2048
	s_add_i32 m0, s2, 0xa000
	s_nop 0
	global_load_lds_dwordx4 v132, s[28:29]
	ds_read_b128 v[202:205], v155 offset:3072
	ds_read_b128 v[206:209], v155 offset:4096
	ds_read_b128 v[210:213], v155 offset:5120
	s_add_u32 s30, s28, 0x20000
	s_addc_u32 s31, s29, 0
	s_add_i32 m0, s2, 0xb000
	s_nop 0
	global_load_lds_dwordx4 v132, s[30:31]
	ds_read_b128 v[214:217], v155 offset:6144
	ds_read_b128 v[218:221], v155 offset:7168
	ds_read_b128 v[156:159], v153 offset:0
	s_add_u32 s30, s28, 0x80000
	s_addc_u32 s31, s29, 0
	s_add_i32 m0, s2, 0xe000
	s_nop 0
	global_load_lds_dwordx4 v132, s[30:31]
	ds_read_b128 v[160:163], v153 offset:1024
	ds_read_b128 v[164:167], v153 offset:2048
	ds_read_b128 v[168:171], v153 offset:3072
	s_add_u32 s30, s28, 0xa0000
	s_addc_u32 s31, s29, 0
	s_add_i32 m0, s2, 0xf000
	s_nop 0
	global_load_lds_dwordx4 v132, s[30:31]
	ds_read_b128 v[174:177], v153 offset:16384
	ds_read_b128 v[178:181], v153 offset:17408
	ds_read_b128 v[182:185], v153 offset:18432
	s_add_u32 s34, s28, 0x80
	s_addc_u32 s35, s29, 0
	s_cmp_eq_u32 s49, 15
	s_cselect_b32 s34, s50, s34
	s_cselect_b32 s35, s51, s35
	s_add_i32 m0, s2, 0x0
	s_nop 0
	global_load_lds_dwordx4 v136, s[34:35]
	ds_read_b128 v[186:189], v153 offset:19456
	ds_read_b128 v[222:225], v155 offset:16384
	ds_read_b128 v[226:229], v155 offset:17408
	s_add_u32 s30, s34, 0x20000
	s_addc_u32 s31, s35, 0
	s_add_i32 m0, s2, 0x1000
	s_nop 0
	global_load_lds_dwordx4 v136, s[30:31]
	ds_read_b128 v[230:233], v155 offset:18432
	ds_read_b128 v[234:237], v155 offset:19456
	ds_read_b128 v[238:241], v155 offset:20480
	s_add_u32 s30, s34, 0x80000
	s_addc_u32 s31, s35, 0
	s_add_i32 m0, s2, 0x4000
	s_nop 0
	global_load_lds_dwordx4 v136, s[30:31]
	ds_read_b128 v[242:245], v155 offset:21504
	ds_read_b128 v[246:249], v155 offset:22528
	ds_read_b128 v[250:253], v155 offset:23552
	s_add_u32 s30, s34, 0xa0000
	s_addc_u32 s31, s35, 0
	s_add_i32 m0, s2, 0x5000
	s_nop 0
	global_load_lds_dwordx4 v136, s[30:31]
	s_add_u32 s28, s28, 0x80
	s_addc_u32 s29, s29, 0
	s_waitcnt vmcnt(8) lgkmcnt(0)
	s_barrier
	v_mfma_f32_16x16x32_bf16 v[126:129], v[156:159], v[190:193], v[126:129]
	v_mfma_f32_16x16x32_bf16 v[126:129], v[160:163], v[194:197], v[126:129]
	v_mfma_f32_16x16x32_bf16 v[122:125], v[168:171], v[194:197], v[122:125]
	v_mfma_f32_16x16x32_bf16 v[122:125], v[164:167], v[190:193], v[122:125]
	v_mfma_f32_16x16x32_bf16 v[118:121], v[174:177], v[190:193], v[118:121]
	v_mfma_f32_16x16x32_bf16 v[118:121], v[178:181], v[194:197], v[118:121]
	v_mfma_f32_16x16x32_bf16 v[114:117], v[186:189], v[194:197], v[114:117]
	v_mfma_f32_16x16x32_bf16 v[114:117], v[182:185], v[190:193], v[114:117]
	v_mfma_f32_16x16x32_bf16 v[98:101], v[182:185], v[198:201], v[98:101]
	v_mfma_f32_16x16x32_bf16 v[98:101], v[186:189], v[202:205], v[98:101]
	v_mfma_f32_16x16x32_bf16 v[102:105], v[178:181], v[202:205], v[102:105]
	v_mfma_f32_16x16x32_bf16 v[102:105], v[174:177], v[198:201], v[102:105]
	v_mfma_f32_16x16x32_bf16 v[106:109], v[164:167], v[198:201], v[106:109]
	v_mfma_f32_16x16x32_bf16 v[106:109], v[168:171], v[202:205], v[106:109]
	v_mfma_f32_16x16x32_bf16 v[110:113], v[160:163], v[202:205], v[110:113]
	v_mfma_f32_16x16x32_bf16 v[110:113], v[156:159], v[198:201], v[110:113]
	v_mfma_f32_16x16x32_bf16 v[94:97], v[156:159], v[206:209], v[94:97]
	v_mfma_f32_16x16x32_bf16 v[94:97], v[160:163], v[210:213], v[94:97]
	v_mfma_f32_16x16x32_bf16 v[90:93], v[168:171], v[210:213], v[90:93]
	v_mfma_f32_16x16x32_bf16 v[90:93], v[164:167], v[206:209], v[90:93]
	v_mfma_f32_16x16x32_bf16 v[86:89], v[174:177], v[206:209], v[86:89]
	v_mfma_f32_16x16x32_bf16 v[86:89], v[178:181], v[210:213], v[86:89]
	v_mfma_f32_16x16x32_bf16 v[82:85], v[186:189], v[210:213], v[82:85]
	v_mfma_f32_16x16x32_bf16 v[82:85], v[182:185], v[206:209], v[82:85]
	v_mfma_f32_16x16x32_bf16 v[66:69], v[182:185], v[214:217], v[66:69]
	v_mfma_f32_16x16x32_bf16 v[66:69], v[186:189], v[218:221], v[66:69]
	v_mfma_f32_16x16x32_bf16 v[70:73], v[178:181], v[218:221], v[70:73]
	v_mfma_f32_16x16x32_bf16 v[70:73], v[174:177], v[214:217], v[70:73]
	v_mfma_f32_16x16x32_bf16 v[74:77], v[164:167], v[214:217], v[74:77]
	v_mfma_f32_16x16x32_bf16 v[74:77], v[168:171], v[218:221], v[74:77]
	v_mfma_f32_16x16x32_bf16 v[78:81], v[160:163], v[218:221], v[78:81]
	v_mfma_f32_16x16x32_bf16 v[78:81], v[156:159], v[214:217], v[78:81]
	v_mfma_f32_16x16x32_bf16 v[62:65], v[156:159], v[222:225], v[62:65]
	v_mfma_f32_16x16x32_bf16 v[62:65], v[160:163], v[226:229], v[62:65]
	v_mfma_f32_16x16x32_bf16 v[58:61], v[168:171], v[226:229], v[58:61]
	v_mfma_f32_16x16x32_bf16 v[58:61], v[164:167], v[222:225], v[58:61]
	v_mfma_f32_16x16x32_bf16 v[54:57], v[174:177], v[222:225], v[54:57]
	v_mfma_f32_16x16x32_bf16 v[54:57], v[178:181], v[226:229], v[54:57]
	v_mfma_f32_16x16x32_bf16 v[50:53], v[186:189], v[226:229], v[50:53]
	v_mfma_f32_16x16x32_bf16 v[50:53], v[182:185], v[222:225], v[50:53]
	v_mfma_f32_16x16x32_bf16 v[34:37], v[182:185], v[230:233], v[34:37]
	v_mfma_f32_16x16x32_bf16 v[34:37], v[186:189], v[234:237], v[34:37]
	v_mfma_f32_16x16x32_bf16 v[38:41], v[178:181], v[234:237], v[38:41]
	v_mfma_f32_16x16x32_bf16 v[38:41], v[174:177], v[230:233], v[38:41]
	v_mfma_f32_16x16x32_bf16 v[42:45], v[164:167], v[230:233], v[42:45]
	v_mfma_f32_16x16x32_bf16 v[42:45], v[168:171], v[234:237], v[42:45]
	v_mfma_f32_16x16x32_bf16 v[46:49], v[160:163], v[234:237], v[46:49]
	v_mfma_f32_16x16x32_bf16 v[46:49], v[156:159], v[230:233], v[46:49]
	v_mfma_f32_16x16x32_bf16 v[30:33], v[156:159], v[238:241], v[30:33]
	v_mfma_f32_16x16x32_bf16 v[30:33], v[160:163], v[242:245], v[30:33]
	v_mfma_f32_16x16x32_bf16 v[26:29], v[168:171], v[242:245], v[26:29]
	v_mfma_f32_16x16x32_bf16 v[26:29], v[164:167], v[238:241], v[26:29]
	v_mfma_f32_16x16x32_bf16 v[22:25], v[174:177], v[238:241], v[22:25]
	v_mfma_f32_16x16x32_bf16 v[22:25], v[178:181], v[242:245], v[22:25]
	v_mfma_f32_16x16x32_bf16 v[18:21], v[186:189], v[242:245], v[18:21]
	v_mfma_f32_16x16x32_bf16 v[18:21], v[182:185], v[238:241], v[18:21]
	v_mfma_f32_16x16x32_bf16 v[2:5], v[182:185], v[246:249], v[2:5]
	v_mfma_f32_16x16x32_bf16 v[2:5], v[186:189], v[250:253], v[2:5]
	v_mfma_f32_16x16x32_bf16 v[6:9], v[178:181], v[250:253], v[6:9]
	v_mfma_f32_16x16x32_bf16 v[6:9], v[174:177], v[246:249], v[6:9]
	v_mfma_f32_16x16x32_bf16 v[10:13], v[164:167], v[246:249], v[10:13]
	v_mfma_f32_16x16x32_bf16 v[10:13], v[168:171], v[250:253], v[10:13]
	v_mfma_f32_16x16x32_bf16 v[14:17], v[160:163], v[250:253], v[14:17]
	v_mfma_f32_16x16x32_bf16 v[14:17], v[156:159], v[246:249], v[14:17]
	s_waitcnt vmcnt(0)
	s_barrier
; #define PG8_STAGE(bufoff, gbase, voff) do { _Pragma("unroll") for (int _i = 0; _i < 2; ++_i) \
;         __builtin_amdgcn_global_load_lds((const unsigned*)((const char*)(gbase) + (voff)[_i]), (PG8_LAS unsigned*)(lds + (bufoff) + ldsw + _i * 8192), 16, 0, 0); } while (0)
; #define PG8_LDA(dst, b, h) do { _Pragma("unroll") for (int m = 0; m < 4; ++m) _Pragma("unroll") for (int k = 0; k < 2; ++k) dst[m][k] = *(const PG8_LAS bf16x8*)(lds + PG8_SA(b, h) + aoff + m * 2048 + k * 1024); } while (0)
; #define PG8_LDB(dst, b, h) do { _Pragma("unroll") for (int n = 0; n < 2; ++n) _Pragma("unroll") for (int k = 0; k < 2; ++k) dst[n][k] = *(const PG8_LAS bf16x8*)(lds + PG8_SB(b, h) + boff + n * 2048 + k * 1024); } while (0)
; #define PG8_MMA(ai, bj, At, Bt) do { __builtin_amdgcn_s_setprio(1); _Pragma("unroll") for (int m = 0; m < 4; ++m) _Pragma("unroll") for (int n = 0; n < 2; ++n) _Pragma("unroll") for (int k = 0; k < 2; ++k) \
;         acc[ai][bj][m][n] = __builtin_amdgcn_mfma_f32_16x16x32_bf16(Bt[n][k], At[m][k], acc[ai][bj][m][n], 0, 0, 0); __builtin_amdgcn_s_setprio(0); } while (0)
; #define PG8_WAIT_V(n) asm volatile("s_waitcnt vmcnt(" #n ")" ::: "memory")
; #define PG8_WAIT_L(n) asm volatile("s_waitcnt lgkmcnt(" #n ")" ::: "memory")
; #define PG8_BAR __builtin_amdgcn_s_barrier()
; #define PG8_SCHED __builtin_amdgcn_sched_barrier(0)
; template <class Epi, class Sched, bool ALIGN_EPI>
; __device__ __forceinline__ void gemm_phase(PG8_LAS unsigned char* lds, const Gemm g, const Sched& S, const Epi& E) {
;     ...
;             PG8_LDB(B0, 1, 0); PG8_LDB(B1, 1, 1); PG8_SCHED; PG8_LDA(At, 1, 0); PG8_STAGE(PG8_SA(0, 1), a2 + hstepA, voffA);
;             PG8_WAIT_V(8); PG8_WAIT_L(0); PG8_BAR; PG8_MMA(0, 0, At, B0); PG8_MMA(0, 1, At, B1); PG8_BAR; PG8_SCHED;
;             PG8_LDA(At, 1, 1); PG8_STAGE(PG8_SB(1, 0), b3, voffB); PG8_STAGE(PG8_SB(1, 1), b3 + hstepB, voffB); PG8_STAGE(PG8_SA(1, 0), a3, voffA);
;             PG8_WAIT_V(8); PG8_WAIT_L(0); PG8_BAR; PG8_MMA(1, 0, At, B0); PG8_MMA(1, 1, At, B1); PG8_BAR; PG8_SCHED;
;         }
	ds_read_b128 v[190:193], v155 offset:32768
	ds_read_b128 v[194:197], v155 offset:33792
	ds_read_b128 v[198:201], v155 offset:34816
	s_cmp_eq_u32 s49, 15
	s_cselect_b32 s28, s50, s28
	s_cselect_b32 s29, s51, s29
	s_add_i32 m0, s2, 0x2000
	s_nop 0
	global_load_lds_dwordx4 v132, s[28:29]
	ds_read_b128 v[202:205], v155 offset:35840
	ds_read_b128 v[206:209], v155 offset:36864
	ds_read_b128 v[210:213], v155 offset:37888
	s_add_u32 s30, s28, 0x20000
	s_addc_u32 s31, s29, 0
	s_add_i32 m0, s2, 0x3000
	s_nop 0
	global_load_lds_dwordx4 v132, s[30:31]
	ds_read_b128 v[214:217], v155 offset:38912
	ds_read_b128 v[218:221], v155 offset:39936
	ds_read_b128 v[156:159], v153 offset:32768
	s_add_u32 s30, s28, 0x80000
	s_addc_u32 s31, s29, 0
	s_add_i32 m0, s2, 0x6000
	s_nop 0
	global_load_lds_dwordx4 v132, s[30:31]
	ds_read_b128 v[160:163], v153 offset:33792
	ds_read_b128 v[164:167], v153 offset:34816
	ds_read_b128 v[168:171], v153 offset:35840
	s_add_u32 s30, s28, 0xa0000
	s_addc_u32 s31, s29, 0
	s_add_i32 m0, s2, 0x7000
	s_nop 0
	global_load_lds_dwordx4 v132, s[30:31]
	ds_read_b128 v[174:177], v153 offset:49152
	ds_read_b128 v[178:181], v153 offset:50176
	ds_read_b128 v[182:185], v153 offset:51200
	s_add_u32 s34, s28, 0x80
	s_addc_u32 s35, s29, 0
	s_add_i32 m0, s2, 0x8000
	s_nop 0
	global_load_lds_dwordx4 v136, s[34:35]
	ds_read_b128 v[186:189], v153 offset:52224
	ds_read_b128 v[222:225], v155 offset:49152
	ds_read_b128 v[226:229], v155 offset:50176
	s_add_u32 s30, s34, 0x20000
	s_addc_u32 s31, s35, 0
	s_add_i32 m0, s2, 0x9000
	s_nop 0
	global_load_lds_dwordx4 v136, s[30:31]
	ds_read_b128 v[230:233], v155 offset:51200
	ds_read_b128 v[234:237], v155 offset:52224
	ds_read_b128 v[238:241], v155 offset:53248
	s_add_u32 s30, s34, 0x80000
	s_addc_u32 s31, s35, 0
	s_add_i32 m0, s2, 0xc000
	s_nop 0
	global_load_lds_dwordx4 v136, s[30:31]
	ds_read_b128 v[242:245], v155 offset:54272
	ds_read_b128 v[246:249], v155 offset:55296
	ds_read_b128 v[250:253], v155 offset:56320
	s_add_u32 s30, s34, 0xa0000
	s_addc_u32 s31, s35, 0
	s_add_i32 m0, s2, 0xd000
	s_nop 0
	global_load_lds_dwordx4 v136, s[30:31]
	s_add_u32 s28, s28, 0x80
	s_addc_u32 s29, s29, 0
	s_waitcnt vmcnt(8) lgkmcnt(0)
	s_barrier
	v_mfma_f32_16x16x32_bf16 v[126:129], v[156:159], v[190:193], v[126:129]
	v_mfma_f32_16x16x32_bf16 v[126:129], v[160:163], v[194:197], v[126:129]
	v_mfma_f32_16x16x32_bf16 v[122:125], v[168:171], v[194:197], v[122:125]
	v_mfma_f32_16x16x32_bf16 v[122:125], v[164:167], v[190:193], v[122:125]
	v_mfma_f32_16x16x32_bf16 v[118:121], v[174:177], v[190:193], v[118:121]
	v_mfma_f32_16x16x32_bf16 v[118:121], v[178:181], v[194:197], v[118:121]
	v_mfma_f32_16x16x32_bf16 v[114:117], v[186:189], v[194:197], v[114:117]
	v_mfma_f32_16x16x32_bf16 v[114:117], v[182:185], v[190:193], v[114:117]
	v_mfma_f32_16x16x32_bf16 v[98:101], v[182:185], v[198:201], v[98:101]
	v_mfma_f32_16x16x32_bf16 v[98:101], v[186:189], v[202:205], v[98:101]
	v_mfma_f32_16x16x32_bf16 v[102:105], v[178:181], v[202:205], v[102:105]
	v_mfma_f32_16x16x32_bf16 v[102:105], v[174:177], v[198:201], v[102:105]
	v_mfma_f32_16x16x32_bf16 v[106:109], v[164:167], v[198:201], v[106:109]
	v_mfma_f32_16x16x32_bf16 v[106:109], v[168:171], v[202:205], v[106:109]
	v_mfma_f32_16x16x32_bf16 v[110:113], v[160:163], v[202:205], v[110:113]
	v_mfma_f32_16x16x32_bf16 v[110:113], v[156:159], v[198:201], v[110:113]
	v_mfma_f32_16x16x32_bf16 v[94:97], v[156:159], v[206:209], v[94:97]
	v_mfma_f32_16x16x32_bf16 v[94:97], v[160:163], v[210:213], v[94:97]
	v_mfma_f32_16x16x32_bf16 v[90:93], v[168:171], v[210:213], v[90:93]
	v_mfma_f32_16x16x32_bf16 v[90:93], v[164:167], v[206:209], v[90:93]
	v_mfma_f32_16x16x32_bf16 v[86:89], v[174:177], v[206:209], v[86:89]
	v_mfma_f32_16x16x32_bf16 v[86:89], v[178:181], v[210:213], v[86:89]
	v_mfma_f32_16x16x32_bf16 v[82:85], v[186:189], v[210:213], v[82:85]
	v_mfma_f32_16x16x32_bf16 v[82:85], v[182:185], v[206:209], v[82:85]
	v_mfma_f32_16x16x32_bf16 v[66:69], v[182:185], v[214:217], v[66:69]
	v_mfma_f32_16x16x32_bf16 v[66:69], v[186:189], v[218:221], v[66:69]
	v_mfma_f32_16x16x32_bf16 v[70:73], v[178:181], v[218:221], v[70:73]
	v_mfma_f32_16x16x32_bf16 v[70:73], v[174:177], v[214:217], v[70:73]
	v_mfma_f32_16x16x32_bf16 v[74:77], v[164:167], v[214:217], v[74:77]
	v_mfma_f32_16x16x32_bf16 v[74:77], v[168:171], v[218:221], v[74:77]
	v_mfma_f32_16x16x32_bf16 v[78:81], v[160:163], v[218:221], v[78:81]
	v_mfma_f32_16x16x32_bf16 v[78:81], v[156:159], v[214:217], v[78:81]
	v_mfma_f32_16x16x32_bf16 v[62:65], v[156:159], v[222:225], v[62:65]
	v_mfma_f32_16x16x32_bf16 v[62:65], v[160:163], v[226:229], v[62:65]
	v_mfma_f32_16x16x32_bf16 v[58:61], v[168:171], v[226:229], v[58:61]
	v_mfma_f32_16x16x32_bf16 v[58:61], v[164:167], v[222:225], v[58:61]
	v_mfma_f32_16x16x32_bf16 v[54:57], v[174:177], v[222:225], v[54:57]
	v_mfma_f32_16x16x32_bf16 v[54:57], v[178:181], v[226:229], v[54:57]
	v_mfma_f32_16x16x32_bf16 v[50:53], v[186:189], v[226:229], v[50:53]
	v_mfma_f32_16x16x32_bf16 v[50:53], v[182:185], v[222:225], v[50:53]
	v_mfma_f32_16x16x32_bf16 v[34:37], v[182:185], v[230:233], v[34:37]
	v_mfma_f32_16x16x32_bf16 v[34:37], v[186:189], v[234:237], v[34:37]
	v_mfma_f32_16x16x32_bf16 v[38:41], v[178:181], v[234:237], v[38:41]
	v_mfma_f32_16x16x32_bf16 v[38:41], v[174:177], v[230:233], v[38:41]
	v_mfma_f32_16x16x32_bf16 v[42:45], v[164:167], v[230:233], v[42:45]
	v_mfma_f32_16x16x32_bf16 v[42:45], v[168:171], v[234:237], v[42:45]
	v_mfma_f32_16x16x32_bf16 v[46:49], v[160:163], v[234:237], v[46:49]
	v_mfma_f32_16x16x32_bf16 v[46:49], v[156:159], v[230:233], v[46:49]
	v_mfma_f32_16x16x32_bf16 v[30:33], v[156:159], v[238:241], v[30:33]
	v_mfma_f32_16x16x32_bf16 v[30:33], v[160:163], v[242:245], v[30:33]
	v_mfma_f32_16x16x32_bf16 v[26:29], v[168:171], v[242:245], v[26:29]
	v_mfma_f32_16x16x32_bf16 v[26:29], v[164:167], v[238:241], v[26:29]
	v_mfma_f32_16x16x32_bf16 v[22:25], v[174:177], v[238:241], v[22:25]
	v_mfma_f32_16x16x32_bf16 v[22:25], v[178:181], v[242:245], v[22:25]
	v_mfma_f32_16x16x32_bf16 v[18:21], v[186:189], v[242:245], v[18:21]
	v_mfma_f32_16x16x32_bf16 v[18:21], v[182:185], v[238:241], v[18:21]
	v_mfma_f32_16x16x32_bf16 v[2:5], v[182:185], v[246:249], v[2:5]
	v_mfma_f32_16x16x32_bf16 v[2:5], v[186:189], v[250:253], v[2:5]
	v_mfma_f32_16x16x32_bf16 v[6:9], v[178:181], v[250:253], v[6:9]
	v_mfma_f32_16x16x32_bf16 v[6:9], v[174:177], v[246:249], v[6:9]
	v_mfma_f32_16x16x32_bf16 v[10:13], v[164:167], v[246:249], v[10:13]
	v_mfma_f32_16x16x32_bf16 v[10:13], v[168:171], v[250:253], v[10:13]
	v_mfma_f32_16x16x32_bf16 v[14:17], v[160:163], v[250:253], v[14:17]
	v_mfma_f32_16x16x32_bf16 v[14:17], v[156:159], v[246:249], v[14:17]
	s_add_i32 s49, s49, 1
	s_cmp_lt_u32 s49, 16
	s_cbranch_scc0 .Lp8k_B_exit
	s_waitcnt vmcnt(0)
	s_barrier
	s_branch .Lp8k_B_loop

; #define PG8_BAR __builtin_amdgcn_s_barrier()
; template <class Epi, class Sched, bool ALIGN_EPI>
; __device__ __forceinline__ void gemm_phase(PG8_LAS unsigned char* lds, const Gemm g, const Sched& S, const Epi& E) {
;     ...
;                     for (int n = 0; n < 2; ++n) acc[a][b][m][n] = (f32x4){0.f, 0.f, 0.f, 0.f};
;         cur = nxt; cA = nA; cB = nB; ++ui;
;         if constexpr (ALIGN_EPI) { if (wr == 1) PG8_BAR; }
.Lp9k_B_init:
	s_setprio 1
	s_sub_u32 s28, s26, 0x57f80
	s_subb_u32 s29, s27, 0
	s_sub_u32 s58, s6, 0x58000
	s_subb_u32 s59, s7, 0
	s_cmp_eq_u32 s42, 1
	s_cbranch_scc1 .Lp9k_B_nobar
	s_waitcnt vmcnt(8)
	s_barrier

; #define PG8_STAGE(bufoff, gbase, voff) do { _Pragma("unroll") for (int _i = 0; _i < 2; ++_i) \
;         __builtin_amdgcn_global_load_lds((const unsigned*)((const char*)(gbase) + (voff)[_i]), (PG8_LAS unsigned*)(lds + (bufoff) + ldsw + _i * 8192), 16, 0, 0); } while (0)
; #define PG8_LDA(dst, b, h) do { _Pragma("unroll") for (int m = 0; m < 4; ++m) _Pragma("unroll") for (int k = 0; k < 2; ++k) dst[m][k] = *(const PG8_LAS bf16x8*)(lds + PG8_SA(b, h) + aoff + m * 2048 + k * 1024); } while (0)
; #define PG8_LDB(dst, b, h) do { _Pragma("unroll") for (int n = 0; n < 2; ++n) _Pragma("unroll") for (int k = 0; k < 2; ++k) dst[n][k] = *(const PG8_LAS bf16x8*)(lds + PG8_SB(b, h) + boff + n * 2048 + k * 1024); } while (0)
; #define PG8_MMA(ai, bj, At, Bt) do { __builtin_amdgcn_s_setprio(1); _Pragma("unroll") for (int m = 0; m < 4; ++m) _Pragma("unroll") for (int n = 0; n < 2; ++n) _Pragma("unroll") for (int k = 0; k < 2; ++k) \
;         acc[ai][bj][m][n] = __builtin_amdgcn_mfma_f32_16x16x32_bf16(Bt[n][k], At[m][k], acc[ai][bj][m][n], 0, 0, 0); __builtin_amdgcn_s_setprio(0); } while (0)
; #define PG8_WAIT_V(n) asm volatile("s_waitcnt vmcnt(" #n ")" ::: "memory")
; #define PG8_WAIT_L(n) asm volatile("s_waitcnt lgkmcnt(" #n ")" ::: "memory")
; #define PG8_BAR __builtin_amdgcn_s_barrier()
; #define PG8_SCHED __builtin_amdgcn_sched_barrier(0)
; template <class Epi, class Sched, bool ALIGN_EPI>
; __device__ __forceinline__ void gemm_phase(PG8_LAS unsigned char* lds, const Gemm g, const Sched& S, const Epi& E) {
;     ...
;             PG8_LDB(B0, 0, 0); PG8_LDB(B1, 0, 1); PG8_SCHED; PG8_LDA(At, 0, 0); PG8_STAGE(PG8_SA(1, 1), a1 + hstepA, voffA);
;             PG8_WAIT_V(8); PG8_WAIT_L(0); PG8_BAR; PG8_MMA(0, 0, At, B0); PG8_MMA(0, 1, At, B1); PG8_BAR; PG8_SCHED;
;             PG8_LDA(At, 0, 1); PG8_STAGE(PG8_SB(0, 0), b2, voffB); PG8_STAGE(PG8_SB(0, 1), b2 + hstepB, voffB); PG8_STAGE(PG8_SA(0, 0), a2, voffA);
;             PG8_WAIT_V(8); PG8_WAIT_L(0); PG8_BAR; PG8_MMA(1, 0, At, B0); PG8_MMA(1, 1, At, B1); PG8_BAR; PG8_SCHED;
;             PG8_LDB(B0, 1, 0); PG8_LDB(B1, 1, 1); PG8_SCHED; PG8_LDA(At, 1, 0); PG8_STAGE(PG8_SA(0, 1), a2 + hstepA, voffA);
;             PG8_WAIT_V(8); PG8_WAIT_L(0); PG8_BAR; PG8_MMA(0, 0, At, B0); PG8_MMA(0, 1, At, B1); PG8_BAR; PG8_SCHED;
.Lp9k_B_loop:
	ds_read_b128 v[194:197], v157 offset:0
	ds_read_b128 v[198:201], v157 offset:1024
	ds_read_b128 v[202:205], v157 offset:2048
	s_add_i32 m0, s60, 0xa000
	s_nop 0
	global_load_lds_dwordx4 v134, s[28:29]
	ds_read_b128 v[206:209], v157 offset:3072
	ds_read_b128 v[210:213], v157 offset:4096
	ds_read_b128 v[214:217], v157 offset:5120
	s_add_u32 s30, s28, 0x58000
	s_addc_u32 s31, s29, 0
	s_add_i32 m0, s60, 0xb000
	s_nop 0
	global_load_lds_dwordx4 v134, s[30:31]
	ds_read_b128 v[218:221], v157 offset:6144
	ds_read_b128 v[222:225], v157 offset:7168
	ds_read_b128 v[158:161], v155 offset:0
	s_add_u32 s30, s28, 0x160000
	s_addc_u32 s31, s29, 0
	s_add_i32 m0, s60, 0xe000
	s_nop 0
	global_load_lds_dwordx4 v134, s[30:31]
	ds_read_b128 v[162:165], v155 offset:1024
	ds_read_b128 v[166:169], v155 offset:2048
	ds_read_b128 v[174:177], v155 offset:3072
	s_add_u32 s30, s28, 0x1b8000
	s_addc_u32 s31, s29, 0
	s_add_i32 m0, s60, 0xf000
	s_nop 0
	global_load_lds_dwordx4 v134, s[30:31]
	ds_read_b128 v[178:181], v155 offset:16384
	ds_read_b128 v[182:185], v155 offset:17408
	ds_read_b128 v[186:189], v155 offset:18432
	s_add_u32 s34, s28, 0x80
	s_addc_u32 s35, s29, 0
	s_cmp_eq_u32 s57, 43
	s_cselect_b32 s34, s58, s34
	s_cselect_b32 s35, s59, s35
	s_add_i32 m0, s60, 0x0
	s_nop 0
	global_load_lds_dwordx4 v130, s[34:35]
	ds_read_b128 v[190:193], v155 offset:19456
	ds_read_b128 v[226:229], v157 offset:16384
	ds_read_b128 v[230:233], v157 offset:17408
	s_add_u32 s30, s34, 0x58000
	s_addc_u32 s31, s35, 0
	s_add_i32 m0, s60, 0x1000
	s_nop 0
	global_load_lds_dwordx4 v130, s[30:31]
	ds_read_b128 v[234:237], v157 offset:18432
	ds_read_b128 v[238:241], v157 offset:19456
	ds_read_b128 v[242:245], v157 offset:20480
	s_add_u32 s30, s34, 0x160000
	s_addc_u32 s31, s35, 0
	s_add_i32 m0, s60, 0x4000
	s_nop 0
	global_load_lds_dwordx4 v130, s[30:31]
	ds_read_b128 v[246:249], v157 offset:21504
	ds_read_b128 v[250:253], v157 offset:22528
	ds_read_b128 v[142:145], v157 offset:23552
	s_add_u32 s30, s34, 0x1b8000
	s_addc_u32 s31, s35, 0
	s_add_i32 m0, s60, 0x5000
	s_nop 0
	global_load_lds_dwordx4 v130, s[30:31]
	s_add_u32 s28, s28, 0x80
	s_addc_u32 s29, s29, 0
	s_waitcnt vmcnt(8) lgkmcnt(0)
	s_barrier
	v_mfma_f32_16x16x32_bf16 v[126:129], v[158:161], v[194:197], v[126:129]
	v_mfma_f32_16x16x32_bf16 v[126:129], v[162:165], v[198:201], v[126:129]
	v_mfma_f32_16x16x32_bf16 v[122:125], v[174:177], v[198:201], v[122:125]
	v_mfma_f32_16x16x32_bf16 v[122:125], v[166:169], v[194:197], v[122:125]
	v_mfma_f32_16x16x32_bf16 v[114:117], v[178:181], v[194:197], v[114:117]
	v_mfma_f32_16x16x32_bf16 v[114:117], v[182:185], v[198:201], v[114:117]
	v_mfma_f32_16x16x32_bf16 v[106:109], v[190:193], v[198:201], v[106:109]
	v_mfma_f32_16x16x32_bf16 v[106:109], v[186:189], v[194:197], v[106:109]
	v_mfma_f32_16x16x32_bf16 v[90:93], v[186:189], v[202:205], v[90:93]
	v_mfma_f32_16x16x32_bf16 v[90:93], v[190:193], v[206:209], v[90:93]
	v_mfma_f32_16x16x32_bf16 v[98:101], v[182:185], v[206:209], v[98:101]
	v_mfma_f32_16x16x32_bf16 v[98:101], v[178:181], v[202:205], v[98:101]
	v_mfma_f32_16x16x32_bf16 v[110:113], v[166:169], v[202:205], v[110:113]
	v_mfma_f32_16x16x32_bf16 v[110:113], v[174:177], v[206:209], v[110:113]
	v_mfma_f32_16x16x32_bf16 v[118:121], v[162:165], v[206:209], v[118:121]
	v_mfma_f32_16x16x32_bf16 v[118:121], v[158:161], v[202:205], v[118:121]
	v_mfma_f32_16x16x32_bf16 v[102:105], v[158:161], v[210:213], v[102:105]
	v_mfma_f32_16x16x32_bf16 v[102:105], v[162:165], v[214:217], v[102:105]
	v_mfma_f32_16x16x32_bf16 v[94:97], v[174:177], v[214:217], v[94:97]
	v_mfma_f32_16x16x32_bf16 v[94:97], v[166:169], v[210:213], v[94:97]
	v_mfma_f32_16x16x32_bf16 v[82:85], v[178:181], v[210:213], v[82:85]
	v_mfma_f32_16x16x32_bf16 v[82:85], v[182:185], v[214:217], v[82:85]
	v_mfma_f32_16x16x32_bf16 v[74:77], v[190:193], v[214:217], v[74:77]
	v_mfma_f32_16x16x32_bf16 v[74:77], v[186:189], v[210:213], v[74:77]
	v_mfma_f32_16x16x32_bf16 v[66:69], v[186:189], v[218:221], v[66:69]
	v_mfma_f32_16x16x32_bf16 v[66:69], v[190:193], v[222:225], v[66:69]
	v_mfma_f32_16x16x32_bf16 v[70:73], v[182:185], v[222:225], v[70:73]
	v_mfma_f32_16x16x32_bf16 v[70:73], v[178:181], v[218:221], v[70:73]
	v_mfma_f32_16x16x32_bf16 v[78:81], v[166:169], v[218:221], v[78:81]
	v_mfma_f32_16x16x32_bf16 v[78:81], v[174:177], v[222:225], v[78:81]
	v_mfma_f32_16x16x32_bf16 v[86:89], v[162:165], v[222:225], v[86:89]
	v_mfma_f32_16x16x32_bf16 v[86:89], v[158:161], v[218:221], v[86:89]
	v_mfma_f32_16x16x32_bf16 v[62:65], v[158:161], v[226:229], v[62:65]
	v_mfma_f32_16x16x32_bf16 v[62:65], v[162:165], v[230:233], v[62:65]
	v_mfma_f32_16x16x32_bf16 v[58:61], v[174:177], v[230:233], v[58:61]
	v_mfma_f32_16x16x32_bf16 v[58:61], v[166:169], v[226:229], v[58:61]
	v_mfma_f32_16x16x32_bf16 v[50:53], v[178:181], v[226:229], v[50:53]
	v_mfma_f32_16x16x32_bf16 v[50:53], v[182:185], v[230:233], v[50:53]
	v_mfma_f32_16x16x32_bf16 v[42:45], v[190:193], v[230:233], v[42:45]
	v_mfma_f32_16x16x32_bf16 v[42:45], v[186:189], v[226:229], v[42:45]
	v_mfma_f32_16x16x32_bf16 v[26:29], v[186:189], v[234:237], v[26:29]
	v_mfma_f32_16x16x32_bf16 v[26:29], v[190:193], v[238:241], v[26:29]
	v_mfma_f32_16x16x32_bf16 v[34:37], v[182:185], v[238:241], v[34:37]
	v_mfma_f32_16x16x32_bf16 v[34:37], v[178:181], v[234:237], v[34:37]
	v_mfma_f32_16x16x32_bf16 v[46:49], v[166:169], v[234:237], v[46:49]
	v_mfma_f32_16x16x32_bf16 v[46:49], v[174:177], v[238:241], v[46:49]
	v_mfma_f32_16x16x32_bf16 v[54:57], v[162:165], v[238:241], v[54:57]
	v_mfma_f32_16x16x32_bf16 v[54:57], v[158:161], v[234:237], v[54:57]
	v_mfma_f32_16x16x32_bf16 v[38:41], v[158:161], v[242:245], v[38:41]
	v_mfma_f32_16x16x32_bf16 v[38:41], v[162:165], v[246:249], v[38:41]
	v_mfma_f32_16x16x32_bf16 v[30:33], v[174:177], v[246:249], v[30:33]
	v_mfma_f32_16x16x32_bf16 v[30:33], v[166:169], v[242:245], v[30:33]
	v_mfma_f32_16x16x32_bf16 v[18:21], v[178:181], v[242:245], v[18:21]
	v_mfma_f32_16x16x32_bf16 v[18:21], v[182:185], v[246:249], v[18:21]
	v_mfma_f32_16x16x32_bf16 v[10:13], v[190:193], v[246:249], v[10:13]
	v_mfma_f32_16x16x32_bf16 v[10:13], v[186:189], v[242:245], v[10:13]
	v_mfma_f32_16x16x32_bf16 v[2:5], v[186:189], v[250:253], v[2:5]
	v_mfma_f32_16x16x32_bf16 v[2:5], v[190:193], v[142:145], v[2:5]
	v_mfma_f32_16x16x32_bf16 v[6:9], v[182:185], v[142:145], v[6:9]
	v_mfma_f32_16x16x32_bf16 v[6:9], v[178:181], v[250:253], v[6:9]
	v_mfma_f32_16x16x32_bf16 v[14:17], v[166:169], v[250:253], v[14:17]
	v_mfma_f32_16x16x32_bf16 v[14:17], v[174:177], v[142:145], v[14:17]
	v_mfma_f32_16x16x32_bf16 v[22:25], v[162:165], v[142:145], v[22:25]
	v_mfma_f32_16x16x32_bf16 v[22:25], v[158:161], v[250:253], v[22:25]
	s_waitcnt vmcnt(0)
	s_barrier
; #define PG8_STAGE(bufoff, gbase, voff) do { _Pragma("unroll") for (int _i = 0; _i < 2; ++_i) \
;         __builtin_amdgcn_global_load_lds((const unsigned*)((const char*)(gbase) + (voff)[_i]), (PG8_LAS unsigned*)(lds + (bufoff) + ldsw + _i * 8192), 16, 0, 0); } while (0)
; #define PG8_LDA(dst, b, h) do { _Pragma("unroll") for (int m = 0; m < 4; ++m) _Pragma("unroll") for (int k = 0; k < 2; ++k) dst[m][k] = *(const PG8_LAS bf16x8*)(lds + PG8_SA(b, h) + aoff + m * 2048 + k * 1024); } while (0)
; #define PG8_LDB(dst, b, h) do { _Pragma("unroll") for (int n = 0; n < 2; ++n) _Pragma("unroll") for (int k = 0; k < 2; ++k) dst[n][k] = *(const PG8_LAS bf16x8*)(lds + PG8_SB(b, h) + boff + n * 2048 + k * 1024); } while (0)
; #define PG8_MMA(ai, bj, At, Bt) do { __builtin_amdgcn_s_setprio(1); _Pragma("unroll") for (int m = 0; m < 4; ++m) _Pragma("unroll") for (int n = 0; n < 2; ++n) _Pragma("unroll") for (int k = 0; k < 2; ++k) \
;         acc[ai][bj][m][n] = __builtin_amdgcn_mfma_f32_16x16x32_bf16(Bt[n][k], At[m][k], acc[ai][bj][m][n], 0, 0, 0); __builtin_amdgcn_s_setprio(0); } while (0)
; #define PG8_WAIT_V(n) asm volatile("s_waitcnt vmcnt(" #n ")" ::: "memory")
; #define PG8_WAIT_L(n) asm volatile("s_waitcnt lgkmcnt(" #n ")" ::: "memory")
; #define PG8_BAR __builtin_amdgcn_s_barrier()
; #define PG8_SCHED __builtin_amdgcn_sched_barrier(0)
; template <class Epi, class Sched, bool ALIGN_EPI>
; __device__ __forceinline__ void gemm_phase(PG8_LAS unsigned char* lds, const Gemm g, const Sched& S, const Epi& E) {
;     ...
;             PG8_LDB(B0, 1, 0); PG8_LDB(B1, 1, 1); PG8_SCHED; PG8_LDA(At, 1, 0); PG8_STAGE(PG8_SA(0, 1), a2 + hstepA, voffA);
;             PG8_WAIT_V(8); PG8_WAIT_L(0); PG8_BAR; PG8_MMA(0, 0, At, B0); PG8_MMA(0, 1, At, B1); PG8_BAR; PG8_SCHED;
;             PG8_LDA(At, 1, 1); PG8_STAGE(PG8_SB(1, 0), b3, voffB); PG8_STAGE(PG8_SB(1, 1), b3 + hstepB, voffB); PG8_STAGE(PG8_SA(1, 0), a3, voffA);
;             PG8_WAIT_V(8); PG8_WAIT_L(0); PG8_BAR; PG8_MMA(1, 0, At, B0); PG8_MMA(1, 1, At, B1); PG8_BAR; PG8_SCHED;
;         }
	ds_read_b128 v[194:197], v157 offset:32768
	ds_read_b128 v[198:201], v157 offset:33792
	ds_read_b128 v[202:205], v157 offset:34816
	s_cmp_eq_u32 s57, 43
	s_cselect_b32 s28, s58, s28
	s_cselect_b32 s29, s59, s29
	s_add_i32 m0, s60, 0x2000
	s_nop 0
	global_load_lds_dwordx4 v134, s[28:29]
	ds_read_b128 v[206:209], v157 offset:35840
	ds_read_b128 v[210:213], v157 offset:36864
	ds_read_b128 v[214:217], v157 offset:37888
	s_add_u32 s30, s28, 0x58000
	s_addc_u32 s31, s29, 0
	s_add_i32 m0, s60, 0x3000
	s_nop 0
	global_load_lds_dwordx4 v134, s[30:31]
	ds_read_b128 v[218:221], v157 offset:38912
	ds_read_b128 v[222:225], v157 offset:39936
	ds_read_b128 v[158:161], v155 offset:32768
	s_add_u32 s30, s28, 0x160000
	s_addc_u32 s31, s29, 0
	s_add_i32 m0, s60, 0x6000
	s_nop 0
	global_load_lds_dwordx4 v134, s[30:31]
	ds_read_b128 v[162:165], v155 offset:33792
	ds_read_b128 v[166:169], v155 offset:34816
	ds_read_b128 v[174:177], v155 offset:35840
	s_add_u32 s30, s28, 0x1b8000
	s_addc_u32 s31, s29, 0
	s_add_i32 m0, s60, 0x7000
	s_nop 0
	global_load_lds_dwordx4 v134, s[30:31]
	ds_read_b128 v[178:181], v155 offset:49152
	ds_read_b128 v[182:185], v155 offset:50176
	ds_read_b128 v[186:189], v155 offset:51200
	s_add_u32 s34, s28, 0x80
	s_addc_u32 s35, s29, 0
	s_add_i32 m0, s60, 0x8000
	s_nop 0
	global_load_lds_dwordx4 v130, s[34:35]
	ds_read_b128 v[190:193], v155 offset:52224
	ds_read_b128 v[226:229], v157 offset:49152
	ds_read_b128 v[230:233], v157 offset:50176
	s_add_u32 s30, s34, 0x58000
	s_addc_u32 s31, s35, 0
	s_add_i32 m0, s60, 0x9000
	s_nop 0
	global_load_lds_dwordx4 v130, s[30:31]
	ds_read_b128 v[234:237], v157 offset:51200
	ds_read_b128 v[238:241], v157 offset:52224
	ds_read_b128 v[242:245], v157 offset:53248
	s_add_u32 s30, s34, 0x160000
	s_addc_u32 s31, s35, 0
	s_add_i32 m0, s60, 0xc000
	s_nop 0
	global_load_lds_dwordx4 v130, s[30:31]
	ds_read_b128 v[246:249], v157 offset:54272
	ds_read_b128 v[250:253], v157 offset:55296
	ds_read_b128 v[142:145], v157 offset:56320
	s_add_u32 s30, s34, 0x1b8000
	s_addc_u32 s31, s35, 0
	s_add_i32 m0, s60, 0xd000
	s_nop 0
	global_load_lds_dwordx4 v130, s[30:31]
	s_add_u32 s28, s28, 0x80
	s_addc_u32 s29, s29, 0
	s_waitcnt vmcnt(8) lgkmcnt(0)
	s_barrier
	v_mfma_f32_16x16x32_bf16 v[126:129], v[158:161], v[194:197], v[126:129]
	v_mfma_f32_16x16x32_bf16 v[126:129], v[162:165], v[198:201], v[126:129]
	v_mfma_f32_16x16x32_bf16 v[122:125], v[174:177], v[198:201], v[122:125]
	v_mfma_f32_16x16x32_bf16 v[122:125], v[166:169], v[194:197], v[122:125]
	v_mfma_f32_16x16x32_bf16 v[114:117], v[178:181], v[194:197], v[114:117]
	v_mfma_f32_16x16x32_bf16 v[114:117], v[182:185], v[198:201], v[114:117]
	v_mfma_f32_16x16x32_bf16 v[106:109], v[190:193], v[198:201], v[106:109]
	v_mfma_f32_16x16x32_bf16 v[106:109], v[186:189], v[194:197], v[106:109]
	v_mfma_f32_16x16x32_bf16 v[90:93], v[186:189], v[202:205], v[90:93]
	v_mfma_f32_16x16x32_bf16 v[90:93], v[190:193], v[206:209], v[90:93]
	v_mfma_f32_16x16x32_bf16 v[98:101], v[182:185], v[206:209], v[98:101]
	v_mfma_f32_16x16x32_bf16 v[98:101], v[178:181], v[202:205], v[98:101]
	v_mfma_f32_16x16x32_bf16 v[110:113], v[166:169], v[202:205], v[110:113]
	v_mfma_f32_16x16x32_bf16 v[110:113], v[174:177], v[206:209], v[110:113]
	v_mfma_f32_16x16x32_bf16 v[118:121], v[162:165], v[206:209], v[118:121]
	v_mfma_f32_16x16x32_bf16 v[118:121], v[158:161], v[202:205], v[118:121]
	v_mfma_f32_16x16x32_bf16 v[102:105], v[158:161], v[210:213], v[102:105]
	v_mfma_f32_16x16x32_bf16 v[102:105], v[162:165], v[214:217], v[102:105]
	v_mfma_f32_16x16x32_bf16 v[94:97], v[174:177], v[214:217], v[94:97]
	v_mfma_f32_16x16x32_bf16 v[94:97], v[166:169], v[210:213], v[94:97]
	v_mfma_f32_16x16x32_bf16 v[82:85], v[178:181], v[210:213], v[82:85]
	v_mfma_f32_16x16x32_bf16 v[82:85], v[182:185], v[214:217], v[82:85]
	v_mfma_f32_16x16x32_bf16 v[74:77], v[190:193], v[214:217], v[74:77]
	v_mfma_f32_16x16x32_bf16 v[74:77], v[186:189], v[210:213], v[74:77]
	v_mfma_f32_16x16x32_bf16 v[66:69], v[186:189], v[218:221], v[66:69]
	v_mfma_f32_16x16x32_bf16 v[66:69], v[190:193], v[222:225], v[66:69]
	v_mfma_f32_16x16x32_bf16 v[70:73], v[182:185], v[222:225], v[70:73]
	v_mfma_f32_16x16x32_bf16 v[70:73], v[178:181], v[218:221], v[70:73]
	v_mfma_f32_16x16x32_bf16 v[78:81], v[166:169], v[218:221], v[78:81]
	v_mfma_f32_16x16x32_bf16 v[78:81], v[174:177], v[222:225], v[78:81]
	v_mfma_f32_16x16x32_bf16 v[86:89], v[162:165], v[222:225], v[86:89]
	v_mfma_f32_16x16x32_bf16 v[86:89], v[158:161], v[218:221], v[86:89]
	v_mfma_f32_16x16x32_bf16 v[62:65], v[158:161], v[226:229], v[62:65]
	v_mfma_f32_16x16x32_bf16 v[62:65], v[162:165], v[230:233], v[62:65]
	v_mfma_f32_16x16x32_bf16 v[58:61], v[174:177], v[230:233], v[58:61]
	v_mfma_f32_16x16x32_bf16 v[58:61], v[166:169], v[226:229], v[58:61]
	v_mfma_f32_16x16x32_bf16 v[50:53], v[178:181], v[226:229], v[50:53]
	v_mfma_f32_16x16x32_bf16 v[50:53], v[182:185], v[230:233], v[50:53]
	v_mfma_f32_16x16x32_bf16 v[42:45], v[190:193], v[230:233], v[42:45]
	v_mfma_f32_16x16x32_bf16 v[42:45], v[186:189], v[226:229], v[42:45]
	v_mfma_f32_16x16x32_bf16 v[26:29], v[186:189], v[234:237], v[26:29]
	v_mfma_f32_16x16x32_bf16 v[26:29], v[190:193], v[238:241], v[26:29]
	v_mfma_f32_16x16x32_bf16 v[34:37], v[182:185], v[238:241], v[34:37]
	v_mfma_f32_16x16x32_bf16 v[34:37], v[178:181], v[234:237], v[34:37]
	v_mfma_f32_16x16x32_bf16 v[46:49], v[166:169], v[234:237], v[46:49]
	v_mfma_f32_16x16x32_bf16 v[46:49], v[174:177], v[238:241], v[46:49]
	v_mfma_f32_16x16x32_bf16 v[54:57], v[162:165], v[238:241], v[54:57]
	v_mfma_f32_16x16x32_bf16 v[54:57], v[158:161], v[234:237], v[54:57]
	v_mfma_f32_16x16x32_bf16 v[38:41], v[158:161], v[242:245], v[38:41]
	v_mfma_f32_16x16x32_bf16 v[38:41], v[162:165], v[246:249], v[38:41]
	v_mfma_f32_16x16x32_bf16 v[30:33], v[174:177], v[246:249], v[30:33]
	v_mfma_f32_16x16x32_bf16 v[30:33], v[166:169], v[242:245], v[30:33]
	v_mfma_f32_16x16x32_bf16 v[18:21], v[178:181], v[242:245], v[18:21]
	v_mfma_f32_16x16x32_bf16 v[18:21], v[182:185], v[246:249], v[18:21]
	v_mfma_f32_16x16x32_bf16 v[10:13], v[190:193], v[246:249], v[10:13]
	v_mfma_f32_16x16x32_bf16 v[10:13], v[186:189], v[242:245], v[10:13]
	v_mfma_f32_16x16x32_bf16 v[2:5], v[186:189], v[250:253], v[2:5]
	v_mfma_f32_16x16x32_bf16 v[2:5], v[190:193], v[142:145], v[2:5]
	v_mfma_f32_16x16x32_bf16 v[6:9], v[182:185], v[142:145], v[6:9]
	v_mfma_f32_16x16x32_bf16 v[6:9], v[178:181], v[250:253], v[6:9]
	v_mfma_f32_16x16x32_bf16 v[14:17], v[166:169], v[250:253], v[14:17]
	v_mfma_f32_16x16x32_bf16 v[14:17], v[174:177], v[142:145], v[14:17]
	v_mfma_f32_16x16x32_bf16 v[22:25], v[162:165], v[142:145], v[22:25]
	v_mfma_f32_16x16x32_bf16 v[22:25], v[158:161], v[250:253], v[22:25]
	s_add_i32 s57, s57, 1
	s_cmp_lt_u32 s57, 44
	s_cbranch_scc0 .Lp9k_B_exit
	s_waitcnt vmcnt(0)
	s_barrier
	s_branch .Lp9k_B_loop
